# stick-breaking half-tile weights rewritten by hand: packed f32 adds, causal mask applied to scores (-inf) only on diagonal tiles, same log2-domain algorithm
# speedup vs baseline: 1.0141x; 1.0061x over previous
.LBB0_41:
	s_add_i32 s0, s42, -1
	v_cmp_le_i32_e32 vcc, s2, v198
	s_and_b32 s45, s0, 1
	s_cbranch_vccnz .LBB0_44
	v_cmp_gt_f32_e32 vcc, s58, v172
	s_cmp_eq_u64 vcc, exec
	s_cbranch_scc1 .LBB0_44
	s_mul_i32 s0, s45, 0x8c00
	s_add_i32 s0, s0, 0
	v_add_u32_e32 v0, s0, v189
	v_add_u32_e32 v173, v0, v188
	ds_read_b128 v[66:69], v173
	ds_read_b128 v[174:177], v173 offset:32
	ds_read_b128 v[82:85], v173 offset:8704
	ds_read_b128 v[200:203], v173 offset:8736
	ds_read_b128 v[204:207], v173 offset:64
	ds_read_b128 v[208:211], v173 offset:96
	ds_read_b128 v[212:215], v173 offset:8768
	ds_read_b128 v[216:219], v173 offset:8800
	s_setprio 1
	s_waitcnt lgkmcnt(7)
	v_mfma_f32_32x32x16_bf16 v[66:81], v[66:69], v[98:101], 0
	s_waitcnt lgkmcnt(5)
	v_mfma_f32_32x32x16_bf16 v[82:97], v[82:85], v[98:101], 0
	v_mfma_f32_32x32x16_bf16 v[66:81], v[174:177], v[102:105], v[66:81]
	s_waitcnt lgkmcnt(4)
	v_mfma_f32_32x32x16_bf16 v[82:97], v[200:203], v[102:105], v[82:97]
	s_waitcnt lgkmcnt(3)
	v_mfma_f32_32x32x16_bf16 v[66:81], v[204:207], v[106:109], v[66:81]
	s_waitcnt lgkmcnt(1)
	v_mfma_f32_32x32x16_bf16 v[82:97], v[212:215], v[106:109], v[82:97]
	v_mfma_f32_32x32x16_bf16 v[66:81], v[208:211], v[110:113], v[66:81]
	s_waitcnt lgkmcnt(0)
	v_mfma_f32_32x32x16_bf16 v[82:97], v[216:219], v[110:113], v[82:97]
	s_setprio 0
	ds_read_b128 v[174:177], v173 offset:128
	ds_read_b128 v[200:203], v173 offset:160
	ds_read_b128 v[204:207], v173 offset:8832
	ds_read_b128 v[208:211], v173 offset:8864
	ds_read_b128 v[212:215], v173 offset:192
	ds_read_b128 v[216:219], v173 offset:224
	ds_read_b128 v[220:223], v173 offset:8896
	ds_read_b128 v[224:227], v173 offset:8928
	s_setprio 1
	s_waitcnt lgkmcnt(7)
	v_mfma_f32_32x32x16_bf16 v[66:81], v[174:177], v[114:117], v[66:81]
	s_waitcnt lgkmcnt(5)
	v_mfma_f32_32x32x16_bf16 v[82:97], v[204:207], v[114:117], v[82:97]
	v_mfma_f32_32x32x16_bf16 v[66:81], v[200:203], v[118:121], v[66:81]
	s_waitcnt lgkmcnt(4)
	v_mfma_f32_32x32x16_bf16 v[82:97], v[208:211], v[118:121], v[82:97]
	s_waitcnt lgkmcnt(3)
	v_mfma_f32_32x32x16_bf16 v[66:81], v[212:215], v[122:125], v[66:81]
	s_waitcnt lgkmcnt(1)
	v_mfma_f32_32x32x16_bf16 v[82:97], v[220:223], v[122:125], v[82:97]
	v_mfma_f32_32x32x16_bf16 v[66:81], v[216:219], v[126:129], v[66:81]
	s_waitcnt lgkmcnt(0)
	v_mfma_f32_32x32x16_bf16 v[82:97], v[224:227], v[126:129], v[82:97]
	s_setprio 0
	s_nop 10
	v_mov_b32_e32 v236, 1.0
	v_cmp_gt_i32_e32 vcc, 28, v159
	s_cmp_eq_u64 vcc, 0
	s_cbranch_scc1 .Lstk_nm1
	v_cmp_lt_i32_e64 s[0:1], 0, v159
	v_cmp_lt_i32_e64 s[8:9], 1, v159
	v_cmp_lt_i32_e64 s[10:11], 2, v159
	v_cmp_lt_i32_e64 s[12:13], 3, v159
	v_cndmask_b32_e64 v82, v231, v82, s[0:1]
	v_cndmask_b32_e64 v83, v231, v83, s[8:9]
	v_cndmask_b32_e64 v84, v231, v84, s[10:11]
	v_cndmask_b32_e64 v85, v231, v85, s[12:13]
	v_cmp_lt_i32_e64 s[0:1], 8, v159
	v_cmp_lt_i32_e64 s[8:9], 9, v159
	v_cmp_lt_i32_e64 s[10:11], 10, v159
	v_cmp_lt_i32_e64 s[12:13], 11, v159
	v_cndmask_b32_e64 v86, v231, v86, s[0:1]
	v_cndmask_b32_e64 v87, v231, v87, s[8:9]
	v_cndmask_b32_e64 v88, v231, v88, s[10:11]
	v_cndmask_b32_e64 v89, v231, v89, s[12:13]
	v_cmp_lt_i32_e64 s[0:1], 16, v159
	v_cmp_lt_i32_e64 s[8:9], 17, v159
	v_cmp_lt_i32_e64 s[10:11], 18, v159
	v_cmp_lt_i32_e64 s[12:13], 19, v159
	v_cndmask_b32_e64 v90, v231, v90, s[0:1]
	v_cndmask_b32_e64 v91, v231, v91, s[8:9]
	v_cndmask_b32_e64 v92, v231, v92, s[10:11]
	v_cndmask_b32_e64 v93, v231, v93, s[12:13]
	v_cmp_lt_i32_e64 s[0:1], 24, v159
	v_cmp_lt_i32_e64 s[8:9], 25, v159
	v_cmp_lt_i32_e64 s[10:11], 26, v159
	v_cmp_lt_i32_e64 s[12:13], 27, v159
	v_cndmask_b32_e64 v94, v231, v94, s[0:1]
	v_cndmask_b32_e64 v95, v231, v95, s[8:9]
	v_cndmask_b32_e64 v96, v231, v96, s[10:11]
	v_cndmask_b32_e64 v97, v231, v97, s[12:13]
.Lstk_nm1:
	v_exp_f32_e64 v200, -|v82|
	v_exp_f32_e64 v201, -|v83|
	v_exp_f32_e64 v202, -|v84|
	v_exp_f32_e64 v203, -|v85|
	v_pk_add_f32 v[200:201], v[200:201], v[236:237] op_sel_hi:[1,0]
	v_max_i32_e32 v174, 0, v82
	v_max_i32_e32 v175, 0, v83
	v_log_f32_e32 v200, v200
	v_log_f32_e32 v201, v201
	v_exp_f32_e64 v204, -|v86|
	v_exp_f32_e64 v205, -|v87|
	v_pk_add_f32 v[202:203], v[202:203], v[236:237] op_sel_hi:[1,0]
	v_max_i32_e32 v176, 0, v84
	v_max_i32_e32 v177, 0, v85
	v_log_f32_e32 v202, v202
	v_log_f32_e32 v203, v203
	v_pk_add_f32 v[200:201], v[200:201], v[174:175]
	v_pk_add_f32 v[82:83], v[82:83], v[200:201] neg_lo:[0,1] neg_hi:[0,1]
	v_exp_f32_e64 v206, -|v88|
	v_exp_f32_e64 v207, -|v89|
	v_pk_add_f32 v[204:205], v[204:205], v[236:237] op_sel_hi:[1,0]
	v_max_i32_e32 v174, 0, v86
	v_max_i32_e32 v175, 0, v87
	v_log_f32_e32 v204, v204
	v_log_f32_e32 v205, v205
	v_pk_add_f32 v[202:203], v[202:203], v[176:177]
	v_pk_add_f32 v[84:85], v[84:85], v[202:203] neg_lo:[0,1] neg_hi:[0,1]
	v_exp_f32_e64 v208, -|v90|
	v_exp_f32_e64 v209, -|v91|
	v_pk_add_f32 v[206:207], v[206:207], v[236:237] op_sel_hi:[1,0]
	v_max_i32_e32 v176, 0, v88
	v_max_i32_e32 v177, 0, v89
	v_log_f32_e32 v206, v206
	v_log_f32_e32 v207, v207
	v_pk_add_f32 v[204:205], v[204:205], v[174:175]
	v_pk_add_f32 v[86:87], v[86:87], v[204:205] neg_lo:[0,1] neg_hi:[0,1]
	v_exp_f32_e64 v210, -|v92|
	v_exp_f32_e64 v211, -|v93|
	v_pk_add_f32 v[208:209], v[208:209], v[236:237] op_sel_hi:[1,0]
	v_max_i32_e32 v174, 0, v90
	v_max_i32_e32 v175, 0, v91
	v_log_f32_e32 v208, v208
	v_log_f32_e32 v209, v209
	v_pk_add_f32 v[206:207], v[206:207], v[176:177]
	v_pk_add_f32 v[88:89], v[88:89], v[206:207] neg_lo:[0,1] neg_hi:[0,1]
	v_exp_f32_e64 v212, -|v94|
	v_exp_f32_e64 v213, -|v95|
	v_pk_add_f32 v[210:211], v[210:211], v[236:237] op_sel_hi:[1,0]
	v_max_i32_e32 v176, 0, v92
	v_max_i32_e32 v177, 0, v93
	v_log_f32_e32 v210, v210
	v_log_f32_e32 v211, v211
	v_pk_add_f32 v[208:209], v[208:209], v[174:175]
	v_pk_add_f32 v[90:91], v[90:91], v[208:209] neg_lo:[0,1] neg_hi:[0,1]
	v_exp_f32_e64 v214, -|v96|
	v_exp_f32_e64 v215, -|v97|
	v_pk_add_f32 v[212:213], v[212:213], v[236:237] op_sel_hi:[1,0]
	v_max_i32_e32 v174, 0, v94
	v_max_i32_e32 v175, 0, v95
	v_log_f32_e32 v212, v212
	v_log_f32_e32 v213, v213
	v_pk_add_f32 v[210:211], v[210:211], v[176:177]
	v_pk_add_f32 v[92:93], v[92:93], v[210:211] neg_lo:[0,1] neg_hi:[0,1]
	v_pk_add_f32 v[214:215], v[214:215], v[236:237] op_sel_hi:[1,0]
	v_max_i32_e32 v176, 0, v96
	v_max_i32_e32 v177, 0, v97
	v_log_f32_e32 v214, v214
	v_log_f32_e32 v215, v215
	v_pk_add_f32 v[212:213], v[212:213], v[174:175]
	v_pk_add_f32 v[94:95], v[94:95], v[212:213] neg_lo:[0,1] neg_hi:[0,1]
	v_pk_add_f32 v[214:215], v[214:215], v[176:177]
	v_pk_add_f32 v[96:97], v[96:97], v[214:215] neg_lo:[0,1] neg_hi:[0,1]
	v_pk_add_f32 v[174:175], v[200:201], v[202:203]
	v_add_f32_e32 v216, v174, v175
	v_mov_b32_e32 v220, v216
	v_pk_add_f32 v[176:177], v[204:205], v[206:207]
	v_add_f32_e32 v217, v176, v177
	v_mov_b32_e32 v221, v217
	v_pk_add_f32 v[174:175], v[208:209], v[210:211]
	v_add_f32_e32 v218, v174, v175
	v_mov_b32_e32 v222, v218
	v_pk_add_f32 v[176:177], v[212:213], v[214:215]
	v_add_f32_e32 v219, v176, v177
	v_mov_b32_e32 v223, v219
	s_nop 1
	v_permlane32_swap_b32_e32 v216, v220
	v_permlane32_swap_b32_e32 v217, v221
	v_permlane32_swap_b32_e32 v218, v222
	v_permlane32_swap_b32_e32 v219, v223
	v_add_f32_e32 v216, v216, v220
	v_cndmask_b32_e64 v220, 0, v220, s[4:5]
	v_add_f32_e32 v217, v217, v221
	v_cndmask_b32_e64 v221, 0, v221, s[4:5]
	v_add_f32_e32 v218, v218, v222
	v_cndmask_b32_e64 v222, 0, v222, s[4:5]
	v_add_f32_e32 v219, v219, v223
	v_cndmask_b32_e64 v223, 0, v223, s[4:5]
	v_add_f32_e32 v224, v219, v218
	v_add_f32_e32 v225, v224, v217
	v_add_f32_e32 v183, v225, v216
	v_sub_f32_e32 v182, v172, v183
	v_sub_f32_e32 v233, v172, v223
	v_sub_f32_e32 v232, v233, v215
	v_sub_f32_e32 v229, v232, v214
	v_sub_f32_e32 v228, v229, v213
	v_pk_add_f32 v[96:97], v[96:97], v[232:233]
	v_pk_add_f32 v[94:95], v[94:95], v[228:229]
	v_exp_f32_e32 v96, v96
	v_exp_f32_e32 v97, v97
	v_exp_f32_e32 v94, v94
	v_exp_f32_e32 v95, v95
	v_sub_f32_e32 v227, v172, v219
	v_sub_f32_e32 v177, v227, v222
	v_sub_f32_e32 v176, v177, v211
	v_sub_f32_e32 v235, v176, v210
	v_sub_f32_e32 v234, v235, v209
	v_pk_add_f32 v[92:93], v[92:93], v[176:177]
	v_pk_add_f32 v[90:91], v[90:91], v[234:235]
	v_exp_f32_e32 v92, v92
	v_exp_f32_e32 v93, v93
	v_exp_f32_e32 v90, v90
	v_exp_f32_e32 v91, v91
	v_sub_f32_e32 v226, v172, v224
	v_sub_f32_e32 v233, v226, v221
	v_sub_f32_e32 v232, v233, v207
	v_sub_f32_e32 v229, v232, v206
	v_sub_f32_e32 v228, v229, v205
	v_pk_add_f32 v[88:89], v[88:89], v[232:233]
	v_pk_add_f32 v[86:87], v[86:87], v[228:229]
	v_exp_f32_e32 v88, v88
	v_exp_f32_e32 v89, v89
	v_exp_f32_e32 v86, v86
	v_exp_f32_e32 v87, v87
	v_sub_f32_e32 v227, v172, v225
	v_sub_f32_e32 v177, v227, v220
	v_sub_f32_e32 v176, v177, v203
	v_sub_f32_e32 v235, v176, v202
	v_sub_f32_e32 v234, v235, v201
	v_pk_add_f32 v[84:85], v[84:85], v[176:177]
	v_pk_add_f32 v[82:83], v[82:83], v[234:235]
	v_exp_f32_e32 v84, v84
	v_exp_f32_e32 v85, v85
	v_exp_f32_e32 v82, v82
	v_exp_f32_e32 v83, v83
	v_add_u32_e32 v199, 32, v159
	v_cmp_gt_i32_e32 vcc, 28, v199
	s_cmp_eq_u64 vcc, 0
	s_cbranch_scc1 .Lstk_nm0
	v_cmp_lt_i32_e64 s[0:1], 0, v199
	v_cmp_lt_i32_e64 s[8:9], 1, v199
	v_cmp_lt_i32_e64 s[10:11], 2, v199
	v_cmp_lt_i32_e64 s[12:13], 3, v199
	v_cndmask_b32_e64 v66, v231, v66, s[0:1]
	v_cndmask_b32_e64 v67, v231, v67, s[8:9]
	v_cndmask_b32_e64 v68, v231, v68, s[10:11]
	v_cndmask_b32_e64 v69, v231, v69, s[12:13]
	v_cmp_lt_i32_e64 s[0:1], 8, v199
	v_cmp_lt_i32_e64 s[8:9], 9, v199
	v_cmp_lt_i32_e64 s[10:11], 10, v199
	v_cmp_lt_i32_e64 s[12:13], 11, v199
	v_cndmask_b32_e64 v70, v231, v70, s[0:1]
	v_cndmask_b32_e64 v71, v231, v71, s[8:9]
	v_cndmask_b32_e64 v72, v231, v72, s[10:11]
	v_cndmask_b32_e64 v73, v231, v73, s[12:13]
	v_cmp_lt_i32_e64 s[0:1], 16, v199
	v_cmp_lt_i32_e64 s[8:9], 17, v199
	v_cmp_lt_i32_e64 s[10:11], 18, v199
	v_cmp_lt_i32_e64 s[12:13], 19, v199
	v_cndmask_b32_e64 v74, v231, v74, s[0:1]
	v_cndmask_b32_e64 v75, v231, v75, s[8:9]
	v_cndmask_b32_e64 v76, v231, v76, s[10:11]
	v_cndmask_b32_e64 v77, v231, v77, s[12:13]
	v_cmp_lt_i32_e64 s[0:1], 24, v199
	v_cmp_lt_i32_e64 s[8:9], 25, v199
	v_cmp_lt_i32_e64 s[10:11], 26, v199
	v_cmp_lt_i32_e64 s[12:13], 27, v199
	v_cndmask_b32_e64 v78, v231, v78, s[0:1]
	v_cndmask_b32_e64 v79, v231, v79, s[8:9]
	v_cndmask_b32_e64 v80, v231, v80, s[10:11]
	v_cndmask_b32_e64 v81, v231, v81, s[12:13]
.Lstk_nm0:
	v_exp_f32_e64 v200, -|v66|
	v_exp_f32_e64 v201, -|v67|
	v_exp_f32_e64 v202, -|v68|
	v_exp_f32_e64 v203, -|v69|
	v_pk_add_f32 v[200:201], v[200:201], v[236:237] op_sel_hi:[1,0]
	v_max_i32_e32 v174, 0, v66
	v_max_i32_e32 v175, 0, v67
	v_log_f32_e32 v200, v200
	v_log_f32_e32 v201, v201
	v_exp_f32_e64 v204, -|v70|
	v_exp_f32_e64 v205, -|v71|
	v_pk_add_f32 v[202:203], v[202:203], v[236:237] op_sel_hi:[1,0]
	v_max_i32_e32 v176, 0, v68
	v_max_i32_e32 v177, 0, v69
	v_log_f32_e32 v202, v202
	v_log_f32_e32 v203, v203
	v_pk_add_f32 v[200:201], v[200:201], v[174:175]
	v_pk_add_f32 v[66:67], v[66:67], v[200:201] neg_lo:[0,1] neg_hi:[0,1]
	v_exp_f32_e64 v206, -|v72|
	v_exp_f32_e64 v207, -|v73|
	v_pk_add_f32 v[204:205], v[204:205], v[236:237] op_sel_hi:[1,0]
	v_max_i32_e32 v174, 0, v70
	v_max_i32_e32 v175, 0, v71
	v_log_f32_e32 v204, v204
	v_log_f32_e32 v205, v205
	v_pk_add_f32 v[202:203], v[202:203], v[176:177]
	v_pk_add_f32 v[68:69], v[68:69], v[202:203] neg_lo:[0,1] neg_hi:[0,1]
	v_exp_f32_e64 v208, -|v74|
	v_exp_f32_e64 v209, -|v75|
	v_pk_add_f32 v[206:207], v[206:207], v[236:237] op_sel_hi:[1,0]
	v_max_i32_e32 v176, 0, v72
	v_max_i32_e32 v177, 0, v73
	v_log_f32_e32 v206, v206
	v_log_f32_e32 v207, v207
	v_pk_add_f32 v[204:205], v[204:205], v[174:175]
	v_pk_add_f32 v[70:71], v[70:71], v[204:205] neg_lo:[0,1] neg_hi:[0,1]
	v_exp_f32_e64 v210, -|v76|
	v_exp_f32_e64 v211, -|v77|
	v_pk_add_f32 v[208:209], v[208:209], v[236:237] op_sel_hi:[1,0]
	v_max_i32_e32 v174, 0, v74
	v_max_i32_e32 v175, 0, v75
	v_log_f32_e32 v208, v208
	v_log_f32_e32 v209, v209
	v_pk_add_f32 v[206:207], v[206:207], v[176:177]
	v_pk_add_f32 v[72:73], v[72:73], v[206:207] neg_lo:[0,1] neg_hi:[0,1]
	v_exp_f32_e64 v212, -|v78|
	v_exp_f32_e64 v213, -|v79|
	v_pk_add_f32 v[210:211], v[210:211], v[236:237] op_sel_hi:[1,0]
	v_max_i32_e32 v176, 0, v76
	v_max_i32_e32 v177, 0, v77
	v_log_f32_e32 v210, v210
	v_log_f32_e32 v211, v211
	v_pk_add_f32 v[208:209], v[208:209], v[174:175]
	v_pk_add_f32 v[74:75], v[74:75], v[208:209] neg_lo:[0,1] neg_hi:[0,1]
	v_exp_f32_e64 v214, -|v80|
	v_exp_f32_e64 v215, -|v81|
	v_pk_add_f32 v[212:213], v[212:213], v[236:237] op_sel_hi:[1,0]
	v_max_i32_e32 v174, 0, v78
	v_max_i32_e32 v175, 0, v79
	v_log_f32_e32 v212, v212
	v_log_f32_e32 v213, v213
	v_pk_add_f32 v[210:211], v[210:211], v[176:177]
	v_pk_add_f32 v[76:77], v[76:77], v[210:211] neg_lo:[0,1] neg_hi:[0,1]
	v_pk_add_f32 v[214:215], v[214:215], v[236:237] op_sel_hi:[1,0]
	v_max_i32_e32 v176, 0, v80
	v_max_i32_e32 v177, 0, v81
	v_log_f32_e32 v214, v214
	v_log_f32_e32 v215, v215
	v_pk_add_f32 v[212:213], v[212:213], v[174:175]
	v_pk_add_f32 v[78:79], v[78:79], v[212:213] neg_lo:[0,1] neg_hi:[0,1]
	v_pk_add_f32 v[214:215], v[214:215], v[176:177]
	v_pk_add_f32 v[80:81], v[80:81], v[214:215] neg_lo:[0,1] neg_hi:[0,1]
	v_pk_add_f32 v[174:175], v[200:201], v[202:203]
	v_add_f32_e32 v216, v174, v175
	v_mov_b32_e32 v220, v216
	v_pk_add_f32 v[176:177], v[204:205], v[206:207]
	v_add_f32_e32 v217, v176, v177
	v_mov_b32_e32 v221, v217
	v_pk_add_f32 v[174:175], v[208:209], v[210:211]
	v_add_f32_e32 v218, v174, v175
	v_mov_b32_e32 v222, v218
	v_pk_add_f32 v[176:177], v[212:213], v[214:215]
	v_add_f32_e32 v219, v176, v177
	v_mov_b32_e32 v223, v219
	s_nop 1
	v_permlane32_swap_b32_e32 v216, v220
	v_permlane32_swap_b32_e32 v217, v221
	v_permlane32_swap_b32_e32 v218, v222
	v_permlane32_swap_b32_e32 v219, v223
	v_add_f32_e32 v216, v216, v220
	v_cndmask_b32_e64 v220, 0, v220, s[4:5]
	v_add_f32_e32 v217, v217, v221
	v_cndmask_b32_e64 v221, 0, v221, s[4:5]
	v_add_f32_e32 v218, v218, v222
	v_cndmask_b32_e64 v222, 0, v222, s[4:5]
	v_add_f32_e32 v219, v219, v223
	v_cndmask_b32_e64 v223, 0, v223, s[4:5]
	v_add_f32_e32 v224, v219, v218
	v_add_f32_e32 v225, v224, v217
	v_add_f32_e32 v230, v225, v216
	v_sub_f32_e32 v233, v182, v223
	v_sub_f32_e32 v232, v233, v215
	v_sub_f32_e32 v229, v232, v214
	v_sub_f32_e32 v228, v229, v213
	v_pk_add_f32 v[80:81], v[80:81], v[232:233]
	v_pk_add_f32 v[78:79], v[78:79], v[228:229]
	v_exp_f32_e32 v80, v80
	v_exp_f32_e32 v81, v81
	v_exp_f32_e32 v78, v78
	v_exp_f32_e32 v79, v79
	v_sub_f32_e32 v227, v182, v219
	v_sub_f32_e32 v177, v227, v222
	v_sub_f32_e32 v176, v177, v211
	v_sub_f32_e32 v235, v176, v210
	v_sub_f32_e32 v234, v235, v209
	v_pk_add_f32 v[76:77], v[76:77], v[176:177]
	v_pk_add_f32 v[74:75], v[74:75], v[234:235]
	v_exp_f32_e32 v76, v76
	v_exp_f32_e32 v77, v77
	v_exp_f32_e32 v74, v74
	v_exp_f32_e32 v75, v75
	v_sub_f32_e32 v226, v182, v224
	v_sub_f32_e32 v233, v226, v221
	v_sub_f32_e32 v232, v233, v207
	v_sub_f32_e32 v229, v232, v206
	v_sub_f32_e32 v228, v229, v205
	v_pk_add_f32 v[72:73], v[72:73], v[232:233]
	v_pk_add_f32 v[70:71], v[70:71], v[228:229]
	v_exp_f32_e32 v72, v72
	v_exp_f32_e32 v73, v73
	v_exp_f32_e32 v70, v70
	v_exp_f32_e32 v71, v71
	v_sub_f32_e32 v227, v182, v225
	v_sub_f32_e32 v177, v227, v220
	v_sub_f32_e32 v176, v177, v203
	v_sub_f32_e32 v235, v176, v202
	v_sub_f32_e32 v234, v235, v201
	v_pk_add_f32 v[68:69], v[68:69], v[176:177]
	v_pk_add_f32 v[66:67], v[66:67], v[234:235]
	v_exp_f32_e32 v68, v68
	v_exp_f32_e32 v69, v69
	v_exp_f32_e32 v66, v66
	v_exp_f32_e32 v67, v67
	v_add_f32_e64 v173, -v183, -v230
	v_add_u32_e32 v0, v0, v191
	v_cvt_pk_bf16_f32 v66, v66, v67
	v_cvt_pk_bf16_f32 v67, v68, v69
	v_cvt_pk_bf16_f32 v68, v70, v71
	v_cvt_pk_bf16_f32 v69, v72, v73
	v_cvt_pk_bf16_f32 v70, v74, v75
	v_cvt_pk_bf16_f32 v71, v76, v77
	v_cvt_pk_bf16_f32 v72, v78, v79
	v_cvt_pk_bf16_f32 v73, v80, v81
	v_cvt_pk_bf16_f32 v74, v82, v83
	v_cvt_pk_bf16_f32 v75, v84, v85
	v_cvt_pk_bf16_f32 v76, v86, v87
	v_cvt_pk_bf16_f32 v77, v88, v89
	v_cvt_pk_bf16_f32 v78, v90, v91
	v_cvt_pk_bf16_f32 v79, v92, v93
	v_cvt_pk_bf16_f32 v80, v94, v95
	v_cvt_pk_bf16_f32 v81, v96, v97
	ds_read_b128 v[82:85], v0 offset:17408
	ds_read_b128 v[86:89], v0 offset:22016
	ds_read_b128 v[90:93], v0 offset:26624
	ds_read_b128 v[94:97], v0 offset:31232
	s_setprio 1
	s_waitcnt lgkmcnt(3)
	v_mfma_f32_32x32x16_bf16 v[50:65], v[82:85], v[66:69], v[50:65]
	s_waitcnt lgkmcnt(2)
	v_mfma_f32_32x32x16_bf16 v[34:49], v[86:89], v[66:69], v[34:49]
	s_waitcnt lgkmcnt(1)
	v_mfma_f32_32x32x16_bf16 v[18:33], v[90:93], v[66:69], v[18:33]
	s_waitcnt lgkmcnt(0)
	v_mfma_f32_32x32x16_bf16 v[2:17], v[94:97], v[66:69], v[2:17]
	s_setprio 0
	ds_read_b128 v[66:69], v0 offset:17440
	ds_read_b128 v[82:85], v0 offset:22048
	ds_read_b128 v[86:89], v0 offset:26656
	ds_read_b128 v[90:93], v0 offset:31264
	s_setprio 1
	s_waitcnt lgkmcnt(3)
	v_mfma_f32_32x32x16_bf16 v[50:65], v[66:69], v[70:73], v[50:65]
	s_waitcnt lgkmcnt(2)
	v_mfma_f32_32x32x16_bf16 v[34:49], v[82:85], v[70:73], v[34:49]
	s_waitcnt lgkmcnt(1)
	v_mfma_f32_32x32x16_bf16 v[18:33], v[86:89], v[70:73], v[18:33]
	s_waitcnt lgkmcnt(0)
	v_mfma_f32_32x32x16_bf16 v[2:17], v[90:93], v[70:73], v[2:17]
	s_setprio 0
	ds_read_b128 v[66:69], v0 offset:17472
	ds_read_b128 v[70:73], v0 offset:22080
	ds_read_b128 v[82:85], v0 offset:26688
	ds_read_b128 v[86:89], v0 offset:31296
	s_setprio 1
	s_waitcnt lgkmcnt(3)
	v_mfma_f32_32x32x16_bf16 v[50:65], v[66:69], v[74:77], v[50:65]
	s_waitcnt lgkmcnt(2)
	v_mfma_f32_32x32x16_bf16 v[34:49], v[70:73], v[74:77], v[34:49]
	s_waitcnt lgkmcnt(1)
	v_mfma_f32_32x32x16_bf16 v[18:33], v[82:85], v[74:77], v[18:33]
	s_waitcnt lgkmcnt(0)
	v_mfma_f32_32x32x16_bf16 v[2:17], v[86:89], v[74:77], v[2:17]
	s_setprio 0
	ds_read_b128 v[66:69], v0 offset:17504
	ds_read_b128 v[70:73], v0 offset:22112
	ds_read_b128 v[74:77], v0 offset:26720
	ds_read_b128 v[82:85], v0 offset:31328
	s_setprio 1
	s_waitcnt lgkmcnt(3)
	v_mfma_f32_32x32x16_bf16 v[50:65], v[66:69], v[78:81], v[50:65]
	s_waitcnt lgkmcnt(2)
	v_mfma_f32_32x32x16_bf16 v[34:49], v[70:73], v[78:81], v[34:49]
	s_waitcnt lgkmcnt(1)
	v_mfma_f32_32x32x16_bf16 v[18:33], v[74:77], v[78:81], v[18:33]
	s_waitcnt lgkmcnt(0)
	v_mfma_f32_32x32x16_bf16 v[2:17], v[82:85], v[78:81], v[2:17]
	s_setprio 0
	v_add_f32_e32 v172, v172, v173
